# mix: rel-pos bias table copied to LDS with all loads of a thread in flight (was 3-4 serialized round trips before the first workgroup barrier)
# speedup vs baseline: 1.0034x; 1.0034x over previous
.LBB0_955:
	s_or_b64 exec, exec, s[4:5]
	s_mov_b64 s[10:11], s[66:67]
	s_waitcnt lgkmcnt(0)
	s_barrier
	v_mov_b32_e32 v0, v1
	s_load_dwordx2 s[8:9], s[10:11], 0x100
	s_load_dwordx2 s[6:7], s[10:11], 0xc0
	v_mbcnt_lo_u32_b32 v0, -1, v0
	v_mbcnt_hi_u32_b32 v0, -1, v0
	v_add_u32_e32 v10, s86, v0
	s_movk_i32 s0, 0xae6
	v_cmp_gt_i32_e32 vcc, s0, v10
	s_and_saveexec_b64 s[4:5], vcc
	s_cbranch_execz .LBB0_963
	s_load_dwordx2 s[0:1], s[10:11], 0xd8
	v_readlane_b32 s2, v255, 21
	v_mov_b32_e32 v8, 0xae5
	v_min_u32_e32 v2, v10, v8
	v_add_u32_e32 v3, 0x200, v10
	v_min_u32_e32 v3, v3, v8
	v_add_u32_e32 v4, 0x400, v10
	v_min_u32_e32 v4, v4, v8
	v_add_u32_e32 v5, 0x600, v10
	v_min_u32_e32 v5, v5, v8
	v_add_u32_e32 v6, 0x800, v10
	v_min_u32_e32 v6, v6, v8
	v_add_u32_e32 v7, 0xa00, v10
	v_min_u32_e32 v7, v7, v8
	v_lshlrev_b32_e32 v2, 2, v2
	v_lshlrev_b32_e32 v3, 2, v3
	v_lshlrev_b32_e32 v4, 2, v4
	v_lshlrev_b32_e32 v5, 2, v5
	v_lshlrev_b32_e32 v6, 2, v6
	v_lshlrev_b32_e32 v7, 2, v7
	s_mulk_i32 s2, 0x2b98
	s_waitcnt lgkmcnt(0)
	s_add_u32 s10, s0, s2
	s_addc_u32 s11, s1, 0
	global_load_dword v112, v2, s[10:11]
	global_load_dword v113, v3, s[10:11]
	global_load_dword v114, v4, s[10:11]
	global_load_dword v115, v5, s[10:11]
	global_load_dword v116, v6, s[10:11]
	global_load_dword v117, v7, s[10:11]
	v_add_u32_e32 v2, 0x18000, v2
	v_add_u32_e32 v3, 0x18000, v3
	v_add_u32_e32 v4, 0x18000, v4
	v_add_u32_e32 v5, 0x18000, v5
	v_add_u32_e32 v6, 0x18000, v6
	v_add_u32_e32 v7, 0x18000, v7
	s_waitcnt vmcnt(5)
	ds_write_b32 v2, v112
	s_waitcnt vmcnt(4)
	ds_write_b32 v3, v113
	s_waitcnt vmcnt(3)
	ds_write_b32 v4, v114
	s_waitcnt vmcnt(2)
	ds_write_b32 v5, v115
	s_waitcnt vmcnt(1)
	ds_write_b32 v6, v116
	s_waitcnt vmcnt(0)
	ds_write_b32 v7, v117
